# sample-unit residual epilogue: xor-1/2/4/8 row-sum butterfly via DPP moves (quad_perm, row_half_mirror, row_mirror) instead of ds_bpermute round trips
# speedup vs baseline: 1.0050x; 1.0050x over previous
.LBB0_409:
	s_waitcnt vmcnt(0)
	v_pk_add_f32 v[2:3], v[14:15], v[2:3]
	v_pk_add_f32 v[4:5], v[12:13], v[4:5]
	v_cvt_pk_bf16_f32 v2, v2, v3
	s_nop 0
	v_cvt_pk_bf16_f32 v3, v4, v5
	global_store_dwordx2 v[16:17], v[2:3], off
	v_lshlrev_b32_e32 v0, 16, v2
	v_and_b32_e32 v2, 0xffff0000, v2
	v_lshlrev_b32_e32 v4, 16, v3
	v_and_b32_e32 v3, 0xffff0000, v3
	v_mul_f32_e32 v2, v2, v2
	v_fmac_f32_e32 v2, v0, v0
	v_mul_f32_e32 v0, v3, v3
	v_fmac_f32_e32 v0, v4, v4
	v_and_b32_e32 v3, 64, v174
	v_add_f32_e32 v0, v2, v0
	v_xor_b32_e32 v2, 1, v174
	v_add_u32_e32 v3, 64, v3
	v_cmp_lt_i32_e32 vcc, v2, v3
	s_nop 1
	v_cndmask_b32_e32 v2, v174, v2, vcc
	v_lshlrev_b32_e32 v2, 2, v2
	s_nop 1
	v_mov_b32_dpp v2, v0 quad_perm:[1,0,3,2] row_mask:0xf bank_mask:0xf
	s_waitcnt lgkmcnt(0)
	v_add_f32_e32 v0, v0, v2
	v_xor_b32_e32 v2, 2, v174
	v_cmp_lt_i32_e32 vcc, v2, v3
	s_nop 1
	v_cndmask_b32_e32 v2, v174, v2, vcc
	v_lshlrev_b32_e32 v2, 2, v2
	s_nop 1
	v_mov_b32_dpp v2, v0 quad_perm:[2,3,0,1] row_mask:0xf bank_mask:0xf
	s_waitcnt lgkmcnt(0)
	v_add_f32_e32 v0, v0, v2
	v_xor_b32_e32 v2, 4, v174
	v_cmp_lt_i32_e32 vcc, v2, v3
	s_nop 1
	v_cndmask_b32_e32 v2, v174, v2, vcc
	v_lshlrev_b32_e32 v2, 2, v2
	s_nop 1
	v_mov_b32_dpp v2, v0 row_half_mirror row_mask:0xf bank_mask:0xf
	s_waitcnt lgkmcnt(0)
	v_add_f32_e32 v0, v0, v2
	v_xor_b32_e32 v2, 8, v174
	v_cmp_lt_i32_e32 vcc, v2, v3
	s_nop 1
	v_cndmask_b32_e32 v2, v174, v2, vcc
	v_lshlrev_b32_e32 v2, 2, v2
	s_nop 1
	v_mov_b32_dpp v2, v0 row_mirror row_mask:0xf bank_mask:0xf
	s_and_saveexec_b64 s[6:7], s[4:5]
	s_cbranch_execz .LBB0_411
	s_waitcnt lgkmcnt(0)
	v_add_f32_e32 v0, v0, v2
	v_mul_f32_e32 v0, 0x4f800000, v0
	v_trunc_f32_e32 v0, v0
	v_mul_f32_e32 v2, 0x2f800000, v0
	v_floor_f32_e32 v3, v2
	v_fmac_f32_e32 v0, 0xcf800000, v3
	v_cvt_u32_f32_e32 v2, v0
	v_cvt_u32_f32_e32 v3, v3
	v_lshl_add_u64 v[4:5], v[8:9], 3, s[26:27]
	global_atomic_add_x2 v[4:5], v[2:3], off

.LBB0_447:
	s_waitcnt vmcnt(0)
	v_pk_add_f32 v[2:3], v[12:13], v[2:3]
	v_pk_add_f32 v[4:5], v[10:11], v[4:5]
	v_cvt_pk_bf16_f32 v2, v2, v3
	s_nop 0
	v_cvt_pk_bf16_f32 v3, v4, v5
	global_store_dwordx2 v[16:17], v[2:3], off
	v_lshlrev_b32_e32 v0, 16, v2
	v_and_b32_e32 v2, 0xffff0000, v2
	v_lshlrev_b32_e32 v4, 16, v3
	v_and_b32_e32 v3, 0xffff0000, v3
	v_mul_f32_e32 v2, v2, v2
	v_fmac_f32_e32 v2, v0, v0
	v_mul_f32_e32 v0, v3, v3
	v_fmac_f32_e32 v0, v4, v4
	v_and_b32_e32 v3, 64, v174
	v_add_f32_e32 v0, v2, v0
	v_xor_b32_e32 v2, 1, v174
	v_add_u32_e32 v3, 64, v3
	v_cmp_lt_i32_e32 vcc, v2, v3
	s_nop 1
	v_cndmask_b32_e32 v2, v174, v2, vcc
	v_lshlrev_b32_e32 v2, 2, v2
	s_nop 1
	v_mov_b32_dpp v2, v0 quad_perm:[1,0,3,2] row_mask:0xf bank_mask:0xf
	s_waitcnt lgkmcnt(0)
	v_add_f32_e32 v0, v0, v2
	v_xor_b32_e32 v2, 2, v174
	v_cmp_lt_i32_e32 vcc, v2, v3
	s_nop 1
	v_cndmask_b32_e32 v2, v174, v2, vcc
	v_lshlrev_b32_e32 v2, 2, v2
	s_nop 1
	v_mov_b32_dpp v2, v0 quad_perm:[2,3,0,1] row_mask:0xf bank_mask:0xf
	s_waitcnt lgkmcnt(0)
	v_add_f32_e32 v0, v0, v2
	v_xor_b32_e32 v2, 4, v174
	v_cmp_lt_i32_e32 vcc, v2, v3
	s_nop 1
	v_cndmask_b32_e32 v2, v174, v2, vcc
	v_lshlrev_b32_e32 v2, 2, v2
	s_nop 1
	v_mov_b32_dpp v2, v0 row_half_mirror row_mask:0xf bank_mask:0xf
	s_waitcnt lgkmcnt(0)
	v_add_f32_e32 v0, v0, v2
	v_xor_b32_e32 v2, 8, v174
	v_cmp_lt_i32_e32 vcc, v2, v3
	s_nop 1
	v_cndmask_b32_e32 v2, v174, v2, vcc
	v_lshlrev_b32_e32 v2, 2, v2
	s_nop 1
	v_mov_b32_dpp v2, v0 row_mirror row_mask:0xf bank_mask:0xf
	s_and_saveexec_b64 s[4:5], s[0:1]
	s_cbranch_execz .LBB0_449
	s_waitcnt lgkmcnt(0)
	v_add_f32_e32 v0, v0, v2
	v_mul_f32_e32 v0, 0x4f800000, v0
	v_trunc_f32_e32 v0, v0
	v_mul_f32_e32 v2, 0x2f800000, v0
	v_floor_f32_e32 v3, v2
	v_fmac_f32_e32 v0, 0xcf800000, v3
	v_cvt_u32_f32_e32 v2, v0
	v_cvt_u32_f32_e32 v3, v3
	v_lshl_add_u64 v[4:5], v[8:9], 3, s[26:27]
	global_atomic_add_x2 v[4:5], v[2:3], off
